# hand-written fused NSA compression MLP (P12+P13): 64-row tiles on all 256 CUs, 3-stage LDS-DMA ring, hidden layer kept in LDS, P13 and its grid barrier removed
# speedup vs baseline: 1.1532x; 1.0224x over previous
.LBB0_3907:
	s_cmp_gt_i32 s44, 12
	s_waitcnt lgkmcnt(0)
	s_cselect_b64 s[2:3], -1, 0
	s_cmp_lt_i32 s45, 13
	s_cselect_b64 s[4:5], -1, 0
	s_or_b64 s[2:3], s[2:3], s[4:5]
	s_and_b64 vcc, exec, s[2:3]
	s_cbranch_vccnz .LBB0_4138
	v_mbcnt_hi_u32_b32 v0, -1, v210
	s_lshr_b32 s29, s70, 6
	s_lshl_b32 s88, s70, 4
	v_and_b32_e32 v1, 31, v0
	v_lshrrev_b32_e32 v2, 5, v0
	v_bfe_u32 v3, v0, 1, 3
	s_and_b32 s2, s29, 3
	s_lshr_b32 s3, s29, 2
	s_and_b32 s4, s70, 0x40
	v_and_b32_e32 v4, 48, v0
	v_or_b32_e32 v4, s4, v4
	v_lshrrev_b32_e32 v5, 3, v0
	v_and_b32_e32 v6, 7, v0
	v_lshlrev_b32_e32 v6, 4, v6
	v_xor_b32_e32 v6, v4, v6
	s_lshl_b32 s5, s29, 3
	v_add_u32_e32 v7, s5, v5
	v_lshlrev_b32_e32 v8, 7, v1
	s_lshl_b32 s6, s3, 12
	s_lshl_b32 s7, s2, 12
	s_add_u32 s7, s7, 0x2000
	s_mov_b32 s13, 0
	s_mov_b32 s15, 0
	s_mov_b32 s17, 0
	s_mov_b32 s19, 0
	v_xor_b32_e32 v200, v2, v3
	v_lshl_add_u32 v200, v200, 4, v8
	s_add_u32 s8, s6, 0
	v_add_u32_e32 v128, s8, v200
	s_add_u32 s8, s7, 0
	v_add_u32_e32 v132, s8, v200
	s_add_u32 s8, s6, 49152
	v_add_u32_e32 v136, s8, v200
	s_add_u32 s8, s7, 49152
	v_add_u32_e32 v140, s8, v200
	s_add_u32 s8, s6, 98304
	v_add_u32_e32 v144, s8, v200
	s_add_u32 s8, s7, 98304
	v_add_u32_e32 v148, s8, v200
	v_or_b32_e32 v201, 2, v2
	v_xor_b32_e32 v201, v201, v3
	v_lshl_add_u32 v201, v201, 4, v8
	s_add_u32 s8, s6, 0
	v_add_u32_e32 v129, s8, v201
	s_add_u32 s8, s7, 0
	v_add_u32_e32 v133, s8, v201
	s_add_u32 s8, s6, 49152
	v_add_u32_e32 v137, s8, v201
	s_add_u32 s8, s7, 49152
	v_add_u32_e32 v141, s8, v201
	s_add_u32 s8, s6, 98304
	v_add_u32_e32 v145, s8, v201
	s_add_u32 s8, s7, 98304
	v_add_u32_e32 v149, s8, v201
	v_or_b32_e32 v202, 4, v2
	v_xor_b32_e32 v202, v202, v3
	v_lshl_add_u32 v202, v202, 4, v8
	s_add_u32 s8, s6, 0
	v_add_u32_e32 v130, s8, v202
	s_add_u32 s8, s7, 0
	v_add_u32_e32 v134, s8, v202
	s_add_u32 s8, s6, 49152
	v_add_u32_e32 v138, s8, v202
	s_add_u32 s8, s7, 49152
	v_add_u32_e32 v142, s8, v202
	s_add_u32 s8, s6, 98304
	v_add_u32_e32 v146, s8, v202
	s_add_u32 s8, s7, 98304
	v_add_u32_e32 v150, s8, v202
	v_or_b32_e32 v203, 6, v2
	v_xor_b32_e32 v203, v203, v3
	v_lshl_add_u32 v203, v203, 4, v8
	s_add_u32 s8, s6, 0
	v_add_u32_e32 v131, s8, v203
	s_add_u32 s8, s7, 0
	v_add_u32_e32 v135, s8, v203
	s_add_u32 s8, s6, 49152
	v_add_u32_e32 v139, s8, v203
	s_add_u32 s8, s7, 49152
	v_add_u32_e32 v143, s8, v203
	s_add_u32 s8, s6, 98304
	v_add_u32_e32 v147, s8, v203
	s_add_u32 s8, s7, 98304
	v_add_u32_e32 v151, s8, v203
	s_load_dwordx4 s[48:51], s[0:1], 0x1a8
	s_load_dwordx8 s[52:59], s[0:1], 0x118
	s_load_dwordx2 s[60:61], s[0:1], 0x150
	s_load_dwordx4 s[24:27], s[0:1], 0x1f0
	s_lshl_b32 s8, s22, 9
	v_add_u32_e32 v10, s70, v0
	v_add_u32_e32 v10, s8, v10
	v_cmp_gt_u32_e32 vcc, 0x800, v10
	s_and_saveexec_b64 s[10:11], vcc
	s_cbranch_execz .Lnc_nopad
	v_lshrrev_b32_e32 v11, 6, v10
	v_and_b32_e32 v12, 63, v10
	v_lshlrev_b32_e32 v11, 15, v11
	v_lshl_add_u32 v11, v12, 1, v11
	v_add_u32_e32 v11, 0x7f80, v11
	v_mov_b32_e32 v12, 0
	s_waitcnt lgkmcnt(0)
	global_store_short v11, v12, s[24:25]
	global_store_short v11, v12, s[26:27]
.Lnc_nopad:
	s_or_b64 exec, exec, s[10:11]
	s_waitcnt lgkmcnt(0)
	s_mov_b32 s30, s22
	s_cmpk_ge_u32 s30, 0x100
	s_cbranch_scc1 .Lnc_done
.Lnc_tile:
	s_lshr_b32 s31, s30, 7
	s_and_b32 s34, s30, 0x7f
	s_lshl_b32 s35, s34, 6
	s_cmp_eq_u32 s31, 0
	s_cselect_b64 s[2:3], s[48:49], s[50:51]
	s_cselect_b64 s[4:5], s[52:53], s[56:57]
	s_cselect_b64 s[6:7], s[54:55], s[58:59]
	s_cselect_b64 s[20:21], s[24:25], s[26:27]
	v_add_u32_e32 v20, s35, v7
	v_min_u32_e32 v20, 0x1fdf, v20
	v_and_b32_e32 v21, 3, v20
	v_lshrrev_b32_e32 v22, 2, v20
	s_mov_b32 s8, 0x80808081
	v_mul_hi_u32 v23, v22, s8
	v_lshrrev_b32_e32 v23, 7, v23
	v_mul_u32_u24_e32 v24, 0xff, v23
	v_sub_u32_e32 v24, v22, v24
	v_lshlrev_b32_e32 v12, 12, v23
	v_lshl_add_u32 v12, v24, 4, v12
	v_lshlrev_b32_e32 v12, 9, v12
	v_lshl_add_u32 v12, v21, 7, v12
	v_add_u32_e32 v12, v12, v6
	v_mov_b32_e32 v13, 0
	v_lshl_add_u64 v[152:153], v[12:13], 0, s[2:3]
	v_lshl_add_u32 v12, v7, 12, v6
	v_lshl_add_u64 v[154:155], v[12:13], 0, s[4:5]
	v_add_u32_e32 v12, 0x40000, v12
	v_lshl_add_u64 v[156:157], v[12:13], 0, s[4:5]
	v_lshl_add_u32 v12, v7, 8, v6
	v_lshl_add_u64 v[158:159], v[12:13], 0, s[6:7]
	s_and_b32 s8, s29, 3
	s_lshl_b32 s8, s8, 7
	s_lshl_b32 s9, s31, 13
	s_add_u32 s8, s8, s9
	v_lshl_add_u32 v12, v1, 2, s8
	v_lshl_add_u64 v[14:15], v[12:13], 0, s[60:61]
	v_add_co_u32_e32 v26, vcc, 0x1000, v14
	s_nop 1
	v_addc_co_u32_e32 v27, vcc, 0, v15, vcc
	s_barrier
	s_mov_b32 s12, 0
	s_mov_b32 s14, 512
	s_mov_b32 s16, 0
	s_mov_b32 s18, 128
	s_add_u32 m0, s88, 0
	v_lshl_add_u64 v[160:161], v[152:153], 0, s[12:13]
	global_load_lds_dwordx4 v[160:161], off
	s_add_u32 m0, s88, 8192
	v_lshl_add_u64 v[162:163], v[154:155], 0, s[16:17]
	global_load_lds_dwordx4 v[162:163], off
	s_add_u32 m0, s88, 16384
	v_lshl_add_u64 v[164:165], v[156:157], 0, s[16:17]
	global_load_lds_dwordx4 v[164:165], off
	s_add_u32 m0, s88, 24576
	v_lshl_add_u64 v[160:161], v[152:153], 0, s[14:15]
	global_load_lds_dwordx4 v[160:161], off
	s_add_u32 m0, s88, 32768
	v_lshl_add_u64 v[162:163], v[154:155], 0, s[18:19]
	global_load_lds_dwordx4 v[162:163], off
	s_add_u32 m0, s88, 40960
	v_lshl_add_u64 v[164:165], v[156:157], 0, s[18:19]
	global_load_lds_dwordx4 v[164:165], off
	s_mov_b32 s12, 1024
	s_mov_b32 s14, 1536
	s_mov_b32 s16, 256
	s_mov_b32 s18, 384
	s_add_u32 m0, s88, 49152
	v_lshl_add_u64 v[160:161], v[152:153], 0, s[12:13]
	global_load_lds_dwordx4 v[160:161], off
	s_add_u32 m0, s88, 57344
	v_lshl_add_u64 v[162:163], v[154:155], 0, s[16:17]
	global_load_lds_dwordx4 v[162:163], off
	s_add_u32 m0, s88, 65536
	v_lshl_add_u64 v[164:165], v[156:157], 0, s[16:17]
	global_load_lds_dwordx4 v[164:165], off
	s_add_u32 m0, s88, 73728
	v_lshl_add_u64 v[160:161], v[152:153], 0, s[14:15]
	global_load_lds_dwordx4 v[160:161], off
	s_add_u32 m0, s88, 81920
	v_lshl_add_u64 v[162:163], v[154:155], 0, s[18:19]
	global_load_lds_dwordx4 v[162:163], off
	s_add_u32 m0, s88, 90112
	v_lshl_add_u64 v[164:165], v[156:157], 0, s[18:19]
	global_load_lds_dwordx4 v[164:165], off
	global_load_dword v168, v[14:15], off
	global_load_dword v169, v[14:15], off offset:512
	global_load_dword v170, v[14:15], off offset:1024
	global_load_dword v171, v[14:15], off offset:1536
	global_load_dword v172, v[14:15], off offset:2048
	global_load_dword v173, v[14:15], off offset:2560
	global_load_dword v174, v[14:15], off offset:3072
	global_load_dword v175, v[14:15], off offset:3584
	global_load_dword v176, v[26:27], off
	global_load_dword v177, v[26:27], off offset:512
	global_load_dword v178, v[26:27], off offset:1024
	global_load_dword v179, v[26:27], off offset:1536
	global_load_dword v180, v[26:27], off offset:2048
	global_load_dword v181, v[26:27], off offset:2560
	global_load_dword v182, v[26:27], off offset:3072
	global_load_dword v183, v[26:27], off offset:3584
	s_waitcnt vmcnt(22)
	s_barrier
	s_mov_b32 s12, 2048
	s_mov_b32 s14, 2560
	s_mov_b32 s16, 512
	s_mov_b32 s18, 640
	s_add_u32 m0, s88, 98304
	v_lshl_add_u64 v[160:161], v[152:153], 0, s[12:13]
	global_load_lds_dwordx4 v[160:161], off
	s_add_u32 m0, s88, 106496
	v_lshl_add_u64 v[162:163], v[154:155], 0, s[16:17]
	global_load_lds_dwordx4 v[162:163], off
	s_add_u32 m0, s88, 114688
	v_lshl_add_u64 v[164:165], v[156:157], 0, s[16:17]
	global_load_lds_dwordx4 v[164:165], off
	s_add_u32 m0, s88, 122880
	v_lshl_add_u64 v[160:161], v[152:153], 0, s[14:15]
	global_load_lds_dwordx4 v[160:161], off
	s_add_u32 m0, s88, 131072
	v_lshl_add_u64 v[162:163], v[154:155], 0, s[18:19]
	global_load_lds_dwordx4 v[162:163], off
	s_add_u32 m0, s88, 139264
	v_lshl_add_u64 v[164:165], v[156:157], 0, s[18:19]
	global_load_lds_dwordx4 v[164:165], off
	ds_read_b128 v[64:67], v128
	ds_read_b128 v[68:71], v132
	ds_read_b128 v[72:75], v129
	ds_read_b128 v[76:79], v133
	ds_read_b128 v[80:83], v130
	ds_read_b128 v[84:87], v134
	ds_read_b128 v[88:91], v131
	ds_read_b128 v[92:95], v135
	ds_read_b128 v[96:99], v128 offset:24576
	ds_read_b128 v[100:103], v132 offset:24576
	ds_read_b128 v[104:107], v129 offset:24576
	ds_read_b128 v[108:111], v133 offset:24576
	ds_read_b128 v[112:115], v130 offset:24576
	ds_read_b128 v[116:119], v134 offset:24576
	ds_read_b128 v[120:123], v131 offset:24576
	ds_read_b128 v[124:127], v135 offset:24576
	s_waitcnt lgkmcnt(14)
	v_mfma_f32_32x32x16_bf16 v[16:31], v[64:67], v[68:71], 0
	s_waitcnt lgkmcnt(12)
	v_mfma_f32_32x32x16_bf16 v[16:31], v[72:75], v[76:79], v[16:31]
	s_waitcnt lgkmcnt(10)
	v_mfma_f32_32x32x16_bf16 v[16:31], v[80:83], v[84:87], v[16:31]
	s_waitcnt lgkmcnt(8)
	v_mfma_f32_32x32x16_bf16 v[16:31], v[88:91], v[92:95], v[16:31]
	s_waitcnt lgkmcnt(6)
	v_mfma_f32_32x32x16_bf16 v[16:31], v[96:99], v[100:103], v[16:31]
	s_waitcnt lgkmcnt(4)
	v_mfma_f32_32x32x16_bf16 v[16:31], v[104:107], v[108:111], v[16:31]
	s_waitcnt lgkmcnt(2)
	v_mfma_f32_32x32x16_bf16 v[16:31], v[112:115], v[116:119], v[16:31]
	s_waitcnt lgkmcnt(0)
	v_mfma_f32_32x32x16_bf16 v[16:31], v[120:123], v[124:127], v[16:31]
	s_waitcnt vmcnt(6)
	s_barrier
	s_mov_b32 s12, 3072
	s_mov_b32 s14, 3584
	s_mov_b32 s16, 768
	s_mov_b32 s18, 896
	s_add_u32 m0, s88, 0
	v_lshl_add_u64 v[160:161], v[152:153], 0, s[12:13]
	global_load_lds_dwordx4 v[160:161], off
	s_add_u32 m0, s88, 8192
	v_lshl_add_u64 v[162:163], v[154:155], 0, s[16:17]
	global_load_lds_dwordx4 v[162:163], off
	s_add_u32 m0, s88, 16384
	v_lshl_add_u64 v[164:165], v[156:157], 0, s[16:17]
	global_load_lds_dwordx4 v[164:165], off
	s_add_u32 m0, s88, 24576
	v_lshl_add_u64 v[160:161], v[152:153], 0, s[14:15]
	global_load_lds_dwordx4 v[160:161], off
	s_add_u32 m0, s88, 32768
	v_lshl_add_u64 v[162:163], v[154:155], 0, s[18:19]
	global_load_lds_dwordx4 v[162:163], off
	s_add_u32 m0, s88, 40960
	v_lshl_add_u64 v[164:165], v[156:157], 0, s[18:19]
	global_load_lds_dwordx4 v[164:165], off
	v_add_f32_e32 v166, 0, v168
	v_add_f32_e32 v166, v166, v169
	v_add_f32_e32 v166, v166, v170
	v_add_f32_e32 v166, v166, v171
	v_add_f32_e32 v166, v166, v172
	v_add_f32_e32 v166, v166, v173
	v_add_f32_e32 v166, v166, v174
	v_add_f32_e32 v166, v166, v175
	v_add_f32_e32 v166, v166, v176
	v_add_f32_e32 v166, v166, v177
	v_add_f32_e32 v166, v166, v178
	v_add_f32_e32 v166, v166, v179
	v_add_f32_e32 v166, v166, v180
	v_add_f32_e32 v166, v166, v181
	v_add_f32_e32 v166, v166, v182
	v_add_f32_e32 v166, v166, v183
	ds_read_b128 v[64:67], v136
	ds_read_b128 v[68:71], v140
	ds_read_b128 v[72:75], v137
	ds_read_b128 v[76:79], v141
	ds_read_b128 v[80:83], v138
	ds_read_b128 v[84:87], v142
	ds_read_b128 v[88:91], v139
	ds_read_b128 v[92:95], v143
	ds_read_b128 v[96:99], v136 offset:24576
	ds_read_b128 v[100:103], v140 offset:24576
	ds_read_b128 v[104:107], v137 offset:24576
	ds_read_b128 v[108:111], v141 offset:24576
	ds_read_b128 v[112:115], v138 offset:24576
	ds_read_b128 v[116:119], v142 offset:24576
	ds_read_b128 v[120:123], v139 offset:24576
	ds_read_b128 v[124:127], v143 offset:24576
	s_waitcnt lgkmcnt(14)
	v_mfma_f32_32x32x16_bf16 v[16:31], v[64:67], v[68:71], v[16:31]
	s_waitcnt lgkmcnt(12)
	v_mfma_f32_32x32x16_bf16 v[16:31], v[72:75], v[76:79], v[16:31]
	s_waitcnt lgkmcnt(10)
	v_mfma_f32_32x32x16_bf16 v[16:31], v[80:83], v[84:87], v[16:31]
	s_waitcnt lgkmcnt(8)
	v_mfma_f32_32x32x16_bf16 v[16:31], v[88:91], v[92:95], v[16:31]
	s_waitcnt lgkmcnt(6)
	v_mfma_f32_32x32x16_bf16 v[16:31], v[96:99], v[100:103], v[16:31]
	s_waitcnt lgkmcnt(4)
	v_mfma_f32_32x32x16_bf16 v[16:31], v[104:107], v[108:111], v[16:31]
	s_waitcnt lgkmcnt(2)
	v_mfma_f32_32x32x16_bf16 v[16:31], v[112:115], v[116:119], v[16:31]
	s_waitcnt lgkmcnt(0)
	v_mfma_f32_32x32x16_bf16 v[16:31], v[120:123], v[124:127], v[16:31]
	s_waitcnt vmcnt(6)
	s_barrier
	s_mov_b32 s12, 4096
	s_mov_b32 s14, 4608
	s_mov_b32 s16, 1024
	s_mov_b32 s18, 1152
	s_add_u32 m0, s88, 49152
	v_lshl_add_u64 v[160:161], v[152:153], 0, s[12:13]
	global_load_lds_dwordx4 v[160:161], off
	s_add_u32 m0, s88, 57344
	v_lshl_add_u64 v[162:163], v[154:155], 0, s[16:17]
	global_load_lds_dwordx4 v[162:163], off
	s_add_u32 m0, s88, 65536
	v_lshl_add_u64 v[164:165], v[156:157], 0, s[16:17]
	global_load_lds_dwordx4 v[164:165], off
	s_add_u32 m0, s88, 73728
	v_lshl_add_u64 v[160:161], v[152:153], 0, s[14:15]
	global_load_lds_dwordx4 v[160:161], off
	s_add_u32 m0, s88, 81920
	v_lshl_add_u64 v[162:163], v[154:155], 0, s[18:19]
	global_load_lds_dwordx4 v[162:163], off
	s_add_u32 m0, s88, 90112
	v_lshl_add_u64 v[164:165], v[156:157], 0, s[18:19]
	global_load_lds_dwordx4 v[164:165], off
	ds_read_b128 v[64:67], v144
	ds_read_b128 v[68:71], v148
	ds_read_b128 v[72:75], v145
	ds_read_b128 v[76:79], v149
	ds_read_b128 v[80:83], v146
	ds_read_b128 v[84:87], v150
	ds_read_b128 v[88:91], v147
	ds_read_b128 v[92:95], v151
	ds_read_b128 v[96:99], v144 offset:24576
	ds_read_b128 v[100:103], v148 offset:24576
	ds_read_b128 v[104:107], v145 offset:24576
	ds_read_b128 v[108:111], v149 offset:24576
	ds_read_b128 v[112:115], v146 offset:24576
	ds_read_b128 v[116:119], v150 offset:24576
	ds_read_b128 v[120:123], v147 offset:24576
	ds_read_b128 v[124:127], v151 offset:24576
	s_waitcnt lgkmcnt(14)
	v_mfma_f32_32x32x16_bf16 v[16:31], v[64:67], v[68:71], v[16:31]
	s_waitcnt lgkmcnt(12)
	v_mfma_f32_32x32x16_bf16 v[16:31], v[72:75], v[76:79], v[16:31]
	s_waitcnt lgkmcnt(10)
	v_mfma_f32_32x32x16_bf16 v[16:31], v[80:83], v[84:87], v[16:31]
	s_waitcnt lgkmcnt(8)
	v_mfma_f32_32x32x16_bf16 v[16:31], v[88:91], v[92:95], v[16:31]
	s_waitcnt lgkmcnt(6)
	v_mfma_f32_32x32x16_bf16 v[16:31], v[96:99], v[100:103], v[16:31]
	s_waitcnt lgkmcnt(4)
	v_mfma_f32_32x32x16_bf16 v[16:31], v[104:107], v[108:111], v[16:31]
	s_waitcnt lgkmcnt(2)
	v_mfma_f32_32x32x16_bf16 v[16:31], v[112:115], v[116:119], v[16:31]
	s_waitcnt lgkmcnt(0)
	v_mfma_f32_32x32x16_bf16 v[16:31], v[120:123], v[124:127], v[16:31]
	s_waitcnt vmcnt(6)
	s_barrier
	s_mov_b32 s12, 5120
	s_mov_b32 s14, 5632
	s_mov_b32 s16, 1280
	s_mov_b32 s18, 1408
	s_add_u32 m0, s88, 98304
	v_lshl_add_u64 v[160:161], v[152:153], 0, s[12:13]
	global_load_lds_dwordx4 v[160:161], off
	s_add_u32 m0, s88, 106496
	v_lshl_add_u64 v[162:163], v[154:155], 0, s[16:17]
	global_load_lds_dwordx4 v[162:163], off
	s_add_u32 m0, s88, 114688
	v_lshl_add_u64 v[164:165], v[156:157], 0, s[16:17]
	global_load_lds_dwordx4 v[164:165], off
	s_add_u32 m0, s88, 122880
	v_lshl_add_u64 v[160:161], v[152:153], 0, s[14:15]
	global_load_lds_dwordx4 v[160:161], off
	s_add_u32 m0, s88, 131072
	v_lshl_add_u64 v[162:163], v[154:155], 0, s[18:19]
	global_load_lds_dwordx4 v[162:163], off
	s_add_u32 m0, s88, 139264
	v_lshl_add_u64 v[164:165], v[156:157], 0, s[18:19]
	global_load_lds_dwordx4 v[164:165], off
	ds_read_b128 v[64:67], v128
	ds_read_b128 v[68:71], v132
	ds_read_b128 v[72:75], v129
	ds_read_b128 v[76:79], v133
	ds_read_b128 v[80:83], v130
	ds_read_b128 v[84:87], v134
	ds_read_b128 v[88:91], v131
	ds_read_b128 v[92:95], v135
	ds_read_b128 v[96:99], v128 offset:24576
	ds_read_b128 v[100:103], v132 offset:24576
	ds_read_b128 v[104:107], v129 offset:24576
	ds_read_b128 v[108:111], v133 offset:24576
	ds_read_b128 v[112:115], v130 offset:24576
	ds_read_b128 v[116:119], v134 offset:24576
	ds_read_b128 v[120:123], v131 offset:24576
	ds_read_b128 v[124:127], v135 offset:24576
	s_waitcnt lgkmcnt(14)
	v_mfma_f32_32x32x16_bf16 v[16:31], v[64:67], v[68:71], v[16:31]
	s_waitcnt lgkmcnt(12)
	v_mfma_f32_32x32x16_bf16 v[16:31], v[72:75], v[76:79], v[16:31]
	s_waitcnt lgkmcnt(10)
	v_mfma_f32_32x32x16_bf16 v[16:31], v[80:83], v[84:87], v[16:31]
	s_waitcnt lgkmcnt(8)
	v_mfma_f32_32x32x16_bf16 v[16:31], v[88:91], v[92:95], v[16:31]
	s_waitcnt lgkmcnt(6)
	v_mfma_f32_32x32x16_bf16 v[16:31], v[96:99], v[100:103], v[16:31]
	s_waitcnt lgkmcnt(4)
	v_mfma_f32_32x32x16_bf16 v[16:31], v[104:107], v[108:111], v[16:31]
	s_waitcnt lgkmcnt(2)
	v_mfma_f32_32x32x16_bf16 v[16:31], v[112:115], v[116:119], v[16:31]
	s_waitcnt lgkmcnt(0)
	v_mfma_f32_32x32x16_bf16 v[16:31], v[120:123], v[124:127], v[16:31]
	s_waitcnt vmcnt(6)
	s_barrier
	s_mov_b32 s12, 6144
	s_mov_b32 s14, 6656
	s_mov_b32 s16, 1536
	s_mov_b32 s18, 1664
	s_add_u32 m0, s88, 0
	v_lshl_add_u64 v[160:161], v[152:153], 0, s[12:13]
	global_load_lds_dwordx4 v[160:161], off
	s_add_u32 m0, s88, 8192
	v_lshl_add_u64 v[162:163], v[154:155], 0, s[16:17]
	global_load_lds_dwordx4 v[162:163], off
	s_add_u32 m0, s88, 16384
	v_lshl_add_u64 v[164:165], v[156:157], 0, s[16:17]
	global_load_lds_dwordx4 v[164:165], off
	s_add_u32 m0, s88, 24576
	v_lshl_add_u64 v[160:161], v[152:153], 0, s[14:15]
	global_load_lds_dwordx4 v[160:161], off
	s_add_u32 m0, s88, 32768
	v_lshl_add_u64 v[162:163], v[154:155], 0, s[18:19]
	global_load_lds_dwordx4 v[162:163], off
	s_add_u32 m0, s88, 40960
	v_lshl_add_u64 v[164:165], v[156:157], 0, s[18:19]
	global_load_lds_dwordx4 v[164:165], off
	ds_read_b128 v[64:67], v136
	ds_read_b128 v[68:71], v140
	ds_read_b128 v[72:75], v137
	ds_read_b128 v[76:79], v141
	ds_read_b128 v[80:83], v138
	ds_read_b128 v[84:87], v142
	ds_read_b128 v[88:91], v139
	ds_read_b128 v[92:95], v143
	ds_read_b128 v[96:99], v136 offset:24576
	ds_read_b128 v[100:103], v140 offset:24576
	ds_read_b128 v[104:107], v137 offset:24576
	ds_read_b128 v[108:111], v141 offset:24576
	ds_read_b128 v[112:115], v138 offset:24576
	ds_read_b128 v[116:119], v142 offset:24576
	ds_read_b128 v[120:123], v139 offset:24576
	ds_read_b128 v[124:127], v143 offset:24576
	s_waitcnt lgkmcnt(14)
	v_mfma_f32_32x32x16_bf16 v[16:31], v[64:67], v[68:71], v[16:31]
	s_waitcnt lgkmcnt(12)
	v_mfma_f32_32x32x16_bf16 v[16:31], v[72:75], v[76:79], v[16:31]
	s_waitcnt lgkmcnt(10)
	v_mfma_f32_32x32x16_bf16 v[16:31], v[80:83], v[84:87], v[16:31]
	s_waitcnt lgkmcnt(8)
	v_mfma_f32_32x32x16_bf16 v[16:31], v[88:91], v[92:95], v[16:31]
	s_waitcnt lgkmcnt(6)
	v_mfma_f32_32x32x16_bf16 v[16:31], v[96:99], v[100:103], v[16:31]
	s_waitcnt lgkmcnt(4)
	v_mfma_f32_32x32x16_bf16 v[16:31], v[104:107], v[108:111], v[16:31]
	s_waitcnt lgkmcnt(2)
	v_mfma_f32_32x32x16_bf16 v[16:31], v[112:115], v[116:119], v[16:31]
	s_waitcnt lgkmcnt(0)
	v_mfma_f32_32x32x16_bf16 v[16:31], v[120:123], v[124:127], v[16:31]
	s_waitcnt vmcnt(6)
	s_barrier
	s_mov_b32 s12, 7168
	s_mov_b32 s14, 7680
	s_mov_b32 s16, 1792
	s_mov_b32 s18, 1920
	s_add_u32 m0, s88, 49152
	v_lshl_add_u64 v[160:161], v[152:153], 0, s[12:13]
	global_load_lds_dwordx4 v[160:161], off
	s_add_u32 m0, s88, 57344
	v_lshl_add_u64 v[162:163], v[154:155], 0, s[16:17]
	global_load_lds_dwordx4 v[162:163], off
	s_add_u32 m0, s88, 65536
	v_lshl_add_u64 v[164:165], v[156:157], 0, s[16:17]
	global_load_lds_dwordx4 v[164:165], off
	s_add_u32 m0, s88, 73728
	v_lshl_add_u64 v[160:161], v[152:153], 0, s[14:15]
	global_load_lds_dwordx4 v[160:161], off
	s_add_u32 m0, s88, 81920
	v_lshl_add_u64 v[162:163], v[154:155], 0, s[18:19]
	global_load_lds_dwordx4 v[162:163], off
	s_add_u32 m0, s88, 90112
	v_lshl_add_u64 v[164:165], v[156:157], 0, s[18:19]
	global_load_lds_dwordx4 v[164:165], off
	ds_read_b128 v[64:67], v144
	ds_read_b128 v[68:71], v148
	ds_read_b128 v[72:75], v145
	ds_read_b128 v[76:79], v149
	ds_read_b128 v[80:83], v146
	ds_read_b128 v[84:87], v150
	ds_read_b128 v[88:91], v147
	ds_read_b128 v[92:95], v151
	ds_read_b128 v[96:99], v144 offset:24576
	ds_read_b128 v[100:103], v148 offset:24576
	ds_read_b128 v[104:107], v145 offset:24576
	ds_read_b128 v[108:111], v149 offset:24576
	ds_read_b128 v[112:115], v146 offset:24576
	ds_read_b128 v[116:119], v150 offset:24576
	ds_read_b128 v[120:123], v147 offset:24576
	ds_read_b128 v[124:127], v151 offset:24576
	s_waitcnt lgkmcnt(14)
	v_mfma_f32_32x32x16_bf16 v[16:31], v[64:67], v[68:71], v[16:31]
	s_waitcnt lgkmcnt(12)
	v_mfma_f32_32x32x16_bf16 v[16:31], v[72:75], v[76:79], v[16:31]
	s_waitcnt lgkmcnt(10)
	v_mfma_f32_32x32x16_bf16 v[16:31], v[80:83], v[84:87], v[16:31]
	s_waitcnt lgkmcnt(8)
	v_mfma_f32_32x32x16_bf16 v[16:31], v[88:91], v[92:95], v[16:31]
	s_waitcnt lgkmcnt(6)
	v_mfma_f32_32x32x16_bf16 v[16:31], v[96:99], v[100:103], v[16:31]
	s_waitcnt lgkmcnt(4)
	v_mfma_f32_32x32x16_bf16 v[16:31], v[104:107], v[108:111], v[16:31]
	s_waitcnt lgkmcnt(2)
	v_mfma_f32_32x32x16_bf16 v[16:31], v[112:115], v[116:119], v[16:31]
	s_waitcnt lgkmcnt(0)
	v_mfma_f32_32x32x16_bf16 v[16:31], v[120:123], v[124:127], v[16:31]
	s_waitcnt vmcnt(6)
	s_barrier
	s_mov_b32 s12, 8192
	s_mov_b32 s14, 8704
	s_mov_b32 s16, 2048
	s_mov_b32 s18, 2176
	s_add_u32 m0, s88, 98304
	v_lshl_add_u64 v[160:161], v[152:153], 0, s[12:13]
	global_load_lds_dwordx4 v[160:161], off
	s_add_u32 m0, s88, 106496
	v_lshl_add_u64 v[162:163], v[154:155], 0, s[16:17]
	global_load_lds_dwordx4 v[162:163], off
	s_add_u32 m0, s88, 114688
	v_lshl_add_u64 v[164:165], v[156:157], 0, s[16:17]
	global_load_lds_dwordx4 v[164:165], off
	s_add_u32 m0, s88, 122880
	v_lshl_add_u64 v[160:161], v[152:153], 0, s[14:15]
	global_load_lds_dwordx4 v[160:161], off
	s_add_u32 m0, s88, 131072
	v_lshl_add_u64 v[162:163], v[154:155], 0, s[18:19]
	global_load_lds_dwordx4 v[162:163], off
	s_add_u32 m0, s88, 139264
	v_lshl_add_u64 v[164:165], v[156:157], 0, s[18:19]
	global_load_lds_dwordx4 v[164:165], off
	ds_read_b128 v[64:67], v128
	ds_read_b128 v[68:71], v132
	ds_read_b128 v[72:75], v129
	ds_read_b128 v[76:79], v133
	ds_read_b128 v[80:83], v130
	ds_read_b128 v[84:87], v134
	ds_read_b128 v[88:91], v131
	ds_read_b128 v[92:95], v135
	ds_read_b128 v[96:99], v128 offset:24576
	ds_read_b128 v[100:103], v132 offset:24576
	ds_read_b128 v[104:107], v129 offset:24576
	ds_read_b128 v[108:111], v133 offset:24576
	ds_read_b128 v[112:115], v130 offset:24576
	ds_read_b128 v[116:119], v134 offset:24576
	ds_read_b128 v[120:123], v131 offset:24576
	ds_read_b128 v[124:127], v135 offset:24576
	s_waitcnt lgkmcnt(14)
	v_mfma_f32_32x32x16_bf16 v[16:31], v[64:67], v[68:71], v[16:31]
	s_waitcnt lgkmcnt(12)
	v_mfma_f32_32x32x16_bf16 v[16:31], v[72:75], v[76:79], v[16:31]
	s_waitcnt lgkmcnt(10)
	v_mfma_f32_32x32x16_bf16 v[16:31], v[80:83], v[84:87], v[16:31]
	s_waitcnt lgkmcnt(8)
	v_mfma_f32_32x32x16_bf16 v[16:31], v[88:91], v[92:95], v[16:31]
	s_waitcnt lgkmcnt(6)
	v_mfma_f32_32x32x16_bf16 v[16:31], v[96:99], v[100:103], v[16:31]
	s_waitcnt lgkmcnt(4)
	v_mfma_f32_32x32x16_bf16 v[16:31], v[104:107], v[108:111], v[16:31]
	s_waitcnt lgkmcnt(2)
	v_mfma_f32_32x32x16_bf16 v[16:31], v[112:115], v[116:119], v[16:31]
	s_waitcnt lgkmcnt(0)
	v_mfma_f32_32x32x16_bf16 v[16:31], v[120:123], v[124:127], v[16:31]
	s_waitcnt vmcnt(6)
	s_barrier
	s_mov_b32 s12, 9216
	s_mov_b32 s14, 9728
	s_mov_b32 s16, 2304
	s_mov_b32 s18, 2432
	s_add_u32 m0, s88, 0
	v_lshl_add_u64 v[160:161], v[152:153], 0, s[12:13]
	global_load_lds_dwordx4 v[160:161], off
	s_add_u32 m0, s88, 8192
	v_lshl_add_u64 v[162:163], v[154:155], 0, s[16:17]
	global_load_lds_dwordx4 v[162:163], off
	s_add_u32 m0, s88, 16384
	v_lshl_add_u64 v[164:165], v[156:157], 0, s[16:17]
	global_load_lds_dwordx4 v[164:165], off
	s_add_u32 m0, s88, 24576
	v_lshl_add_u64 v[160:161], v[152:153], 0, s[14:15]
	global_load_lds_dwordx4 v[160:161], off
	s_add_u32 m0, s88, 32768
	v_lshl_add_u64 v[162:163], v[154:155], 0, s[18:19]
	global_load_lds_dwordx4 v[162:163], off
	s_add_u32 m0, s88, 40960
	v_lshl_add_u64 v[164:165], v[156:157], 0, s[18:19]
	global_load_lds_dwordx4 v[164:165], off
	ds_read_b128 v[64:67], v136
	ds_read_b128 v[68:71], v140
	ds_read_b128 v[72:75], v137
	ds_read_b128 v[76:79], v141
	ds_read_b128 v[80:83], v138
	ds_read_b128 v[84:87], v142
	ds_read_b128 v[88:91], v139
	ds_read_b128 v[92:95], v143
	ds_read_b128 v[96:99], v136 offset:24576
	ds_read_b128 v[100:103], v140 offset:24576
	ds_read_b128 v[104:107], v137 offset:24576
	ds_read_b128 v[108:111], v141 offset:24576
	ds_read_b128 v[112:115], v138 offset:24576
	ds_read_b128 v[116:119], v142 offset:24576
	ds_read_b128 v[120:123], v139 offset:24576
	ds_read_b128 v[124:127], v143 offset:24576
	s_waitcnt lgkmcnt(14)
	v_mfma_f32_32x32x16_bf16 v[16:31], v[64:67], v[68:71], v[16:31]
	s_waitcnt lgkmcnt(12)
	v_mfma_f32_32x32x16_bf16 v[16:31], v[72:75], v[76:79], v[16:31]
	s_waitcnt lgkmcnt(10)
	v_mfma_f32_32x32x16_bf16 v[16:31], v[80:83], v[84:87], v[16:31]
	s_waitcnt lgkmcnt(8)
	v_mfma_f32_32x32x16_bf16 v[16:31], v[88:91], v[92:95], v[16:31]
	s_waitcnt lgkmcnt(6)
	v_mfma_f32_32x32x16_bf16 v[16:31], v[96:99], v[100:103], v[16:31]
	s_waitcnt lgkmcnt(4)
	v_mfma_f32_32x32x16_bf16 v[16:31], v[104:107], v[108:111], v[16:31]
	s_waitcnt lgkmcnt(2)
	v_mfma_f32_32x32x16_bf16 v[16:31], v[112:115], v[116:119], v[16:31]
	s_waitcnt lgkmcnt(0)
	v_mfma_f32_32x32x16_bf16 v[16:31], v[120:123], v[124:127], v[16:31]
	s_waitcnt vmcnt(6)
	s_barrier
	s_mov_b32 s12, 10240
	s_mov_b32 s14, 10752
	s_mov_b32 s16, 2560
	s_mov_b32 s18, 2688
	s_add_u32 m0, s88, 49152
	v_lshl_add_u64 v[160:161], v[152:153], 0, s[12:13]
	global_load_lds_dwordx4 v[160:161], off
	s_add_u32 m0, s88, 57344
	v_lshl_add_u64 v[162:163], v[154:155], 0, s[16:17]
	global_load_lds_dwordx4 v[162:163], off
	s_add_u32 m0, s88, 65536
	v_lshl_add_u64 v[164:165], v[156:157], 0, s[16:17]
	global_load_lds_dwordx4 v[164:165], off
	s_add_u32 m0, s88, 73728
	v_lshl_add_u64 v[160:161], v[152:153], 0, s[14:15]
	global_load_lds_dwordx4 v[160:161], off
	s_add_u32 m0, s88, 81920
	v_lshl_add_u64 v[162:163], v[154:155], 0, s[18:19]
	global_load_lds_dwordx4 v[162:163], off
	s_add_u32 m0, s88, 90112
	v_lshl_add_u64 v[164:165], v[156:157], 0, s[18:19]
	global_load_lds_dwordx4 v[164:165], off
	ds_read_b128 v[64:67], v144
	ds_read_b128 v[68:71], v148
	ds_read_b128 v[72:75], v145
	ds_read_b128 v[76:79], v149
	ds_read_b128 v[80:83], v146
	ds_read_b128 v[84:87], v150
	ds_read_b128 v[88:91], v147
	ds_read_b128 v[92:95], v151
	ds_read_b128 v[96:99], v144 offset:24576
	ds_read_b128 v[100:103], v148 offset:24576
	ds_read_b128 v[104:107], v145 offset:24576
	ds_read_b128 v[108:111], v149 offset:24576
	ds_read_b128 v[112:115], v146 offset:24576
	ds_read_b128 v[116:119], v150 offset:24576
	ds_read_b128 v[120:123], v147 offset:24576
	ds_read_b128 v[124:127], v151 offset:24576
	s_waitcnt lgkmcnt(14)
	v_mfma_f32_32x32x16_bf16 v[16:31], v[64:67], v[68:71], v[16:31]
	s_waitcnt lgkmcnt(12)
	v_mfma_f32_32x32x16_bf16 v[16:31], v[72:75], v[76:79], v[16:31]
	s_waitcnt lgkmcnt(10)
	v_mfma_f32_32x32x16_bf16 v[16:31], v[80:83], v[84:87], v[16:31]
	s_waitcnt lgkmcnt(8)
	v_mfma_f32_32x32x16_bf16 v[16:31], v[88:91], v[92:95], v[16:31]
	s_waitcnt lgkmcnt(6)
	v_mfma_f32_32x32x16_bf16 v[16:31], v[96:99], v[100:103], v[16:31]
	s_waitcnt lgkmcnt(4)
	v_mfma_f32_32x32x16_bf16 v[16:31], v[104:107], v[108:111], v[16:31]
	s_waitcnt lgkmcnt(2)
	v_mfma_f32_32x32x16_bf16 v[16:31], v[112:115], v[116:119], v[16:31]
	s_waitcnt lgkmcnt(0)
	v_mfma_f32_32x32x16_bf16 v[16:31], v[120:123], v[124:127], v[16:31]
	s_waitcnt vmcnt(6)
	s_barrier
	s_mov_b32 s12, 11264
	s_mov_b32 s14, 11776
	s_mov_b32 s16, 2816
	s_mov_b32 s18, 2944
	s_add_u32 m0, s88, 98304
	v_lshl_add_u64 v[160:161], v[152:153], 0, s[12:13]
	global_load_lds_dwordx4 v[160:161], off
	s_add_u32 m0, s88, 106496
	v_lshl_add_u64 v[162:163], v[154:155], 0, s[16:17]
	global_load_lds_dwordx4 v[162:163], off
	s_add_u32 m0, s88, 114688
	v_lshl_add_u64 v[164:165], v[156:157], 0, s[16:17]
	global_load_lds_dwordx4 v[164:165], off
	s_add_u32 m0, s88, 122880
	v_lshl_add_u64 v[160:161], v[152:153], 0, s[14:15]
	global_load_lds_dwordx4 v[160:161], off
	s_add_u32 m0, s88, 131072
	v_lshl_add_u64 v[162:163], v[154:155], 0, s[18:19]
	global_load_lds_dwordx4 v[162:163], off
	s_add_u32 m0, s88, 139264
	v_lshl_add_u64 v[164:165], v[156:157], 0, s[18:19]
	global_load_lds_dwordx4 v[164:165], off
	ds_read_b128 v[64:67], v128
	ds_read_b128 v[68:71], v132
	ds_read_b128 v[72:75], v129
	ds_read_b128 v[76:79], v133
	ds_read_b128 v[80:83], v130
	ds_read_b128 v[84:87], v134
	ds_read_b128 v[88:91], v131
	ds_read_b128 v[92:95], v135
	ds_read_b128 v[96:99], v128 offset:24576
	ds_read_b128 v[100:103], v132 offset:24576
	ds_read_b128 v[104:107], v129 offset:24576
	ds_read_b128 v[108:111], v133 offset:24576
	ds_read_b128 v[112:115], v130 offset:24576
	ds_read_b128 v[116:119], v134 offset:24576
	ds_read_b128 v[120:123], v131 offset:24576
	ds_read_b128 v[124:127], v135 offset:24576
	s_waitcnt lgkmcnt(14)
	v_mfma_f32_32x32x16_bf16 v[16:31], v[64:67], v[68:71], v[16:31]
	s_waitcnt lgkmcnt(12)
	v_mfma_f32_32x32x16_bf16 v[16:31], v[72:75], v[76:79], v[16:31]
	s_waitcnt lgkmcnt(10)
	v_mfma_f32_32x32x16_bf16 v[16:31], v[80:83], v[84:87], v[16:31]
	s_waitcnt lgkmcnt(8)
	v_mfma_f32_32x32x16_bf16 v[16:31], v[88:91], v[92:95], v[16:31]
	s_waitcnt lgkmcnt(6)
	v_mfma_f32_32x32x16_bf16 v[16:31], v[96:99], v[100:103], v[16:31]
	s_waitcnt lgkmcnt(4)
	v_mfma_f32_32x32x16_bf16 v[16:31], v[104:107], v[108:111], v[16:31]
	s_waitcnt lgkmcnt(2)
	v_mfma_f32_32x32x16_bf16 v[16:31], v[112:115], v[116:119], v[16:31]
	s_waitcnt lgkmcnt(0)
	v_mfma_f32_32x32x16_bf16 v[16:31], v[120:123], v[124:127], v[16:31]
	s_waitcnt vmcnt(6)
	s_barrier
	s_mov_b32 s12, 12288
	s_mov_b32 s14, 12800
	s_mov_b32 s16, 3072
	s_mov_b32 s18, 3200
	s_add_u32 m0, s88, 0
	v_lshl_add_u64 v[160:161], v[152:153], 0, s[12:13]
	global_load_lds_dwordx4 v[160:161], off
	s_add_u32 m0, s88, 8192
	v_lshl_add_u64 v[162:163], v[154:155], 0, s[16:17]
	global_load_lds_dwordx4 v[162:163], off
	s_add_u32 m0, s88, 16384
	v_lshl_add_u64 v[164:165], v[156:157], 0, s[16:17]
	global_load_lds_dwordx4 v[164:165], off
	s_add_u32 m0, s88, 24576
	v_lshl_add_u64 v[160:161], v[152:153], 0, s[14:15]
	global_load_lds_dwordx4 v[160:161], off
	s_add_u32 m0, s88, 32768
	v_lshl_add_u64 v[162:163], v[154:155], 0, s[18:19]
	global_load_lds_dwordx4 v[162:163], off
	s_add_u32 m0, s88, 40960
	v_lshl_add_u64 v[164:165], v[156:157], 0, s[18:19]
	global_load_lds_dwordx4 v[164:165], off
	ds_read_b128 v[64:67], v136
	ds_read_b128 v[68:71], v140
	ds_read_b128 v[72:75], v137
	ds_read_b128 v[76:79], v141
	ds_read_b128 v[80:83], v138
	ds_read_b128 v[84:87], v142
	ds_read_b128 v[88:91], v139
	ds_read_b128 v[92:95], v143
	ds_read_b128 v[96:99], v136 offset:24576
	ds_read_b128 v[100:103], v140 offset:24576
	ds_read_b128 v[104:107], v137 offset:24576
	ds_read_b128 v[108:111], v141 offset:24576
	ds_read_b128 v[112:115], v138 offset:24576
	ds_read_b128 v[116:119], v142 offset:24576
	ds_read_b128 v[120:123], v139 offset:24576
	ds_read_b128 v[124:127], v143 offset:24576
	s_waitcnt lgkmcnt(14)
	v_mfma_f32_32x32x16_bf16 v[16:31], v[64:67], v[68:71], v[16:31]
	s_waitcnt lgkmcnt(12)
	v_mfma_f32_32x32x16_bf16 v[16:31], v[72:75], v[76:79], v[16:31]
	s_waitcnt lgkmcnt(10)
	v_mfma_f32_32x32x16_bf16 v[16:31], v[80:83], v[84:87], v[16:31]
	s_waitcnt lgkmcnt(8)
	v_mfma_f32_32x32x16_bf16 v[16:31], v[88:91], v[92:95], v[16:31]
	s_waitcnt lgkmcnt(6)
	v_mfma_f32_32x32x16_bf16 v[16:31], v[96:99], v[100:103], v[16:31]
	s_waitcnt lgkmcnt(4)
	v_mfma_f32_32x32x16_bf16 v[16:31], v[104:107], v[108:111], v[16:31]
	s_waitcnt lgkmcnt(2)
	v_mfma_f32_32x32x16_bf16 v[16:31], v[112:115], v[116:119], v[16:31]
	s_waitcnt lgkmcnt(0)
	v_mfma_f32_32x32x16_bf16 v[16:31], v[120:123], v[124:127], v[16:31]
	s_waitcnt vmcnt(6)
	s_barrier
	s_mov_b32 s12, 13312
	s_mov_b32 s14, 13824
	s_mov_b32 s16, 3328
	s_mov_b32 s18, 3456
	s_add_u32 m0, s88, 49152
	v_lshl_add_u64 v[160:161], v[152:153], 0, s[12:13]
	global_load_lds_dwordx4 v[160:161], off
	s_add_u32 m0, s88, 57344
	v_lshl_add_u64 v[162:163], v[154:155], 0, s[16:17]
	global_load_lds_dwordx4 v[162:163], off
	s_add_u32 m0, s88, 65536
	v_lshl_add_u64 v[164:165], v[156:157], 0, s[16:17]
	global_load_lds_dwordx4 v[164:165], off
	s_add_u32 m0, s88, 73728
	v_lshl_add_u64 v[160:161], v[152:153], 0, s[14:15]
	global_load_lds_dwordx4 v[160:161], off
	s_add_u32 m0, s88, 81920
	v_lshl_add_u64 v[162:163], v[154:155], 0, s[18:19]
	global_load_lds_dwordx4 v[162:163], off
	s_add_u32 m0, s88, 90112
	v_lshl_add_u64 v[164:165], v[156:157], 0, s[18:19]
	global_load_lds_dwordx4 v[164:165], off
	ds_read_b128 v[64:67], v144
	ds_read_b128 v[68:71], v148
	ds_read_b128 v[72:75], v145
	ds_read_b128 v[76:79], v149
	ds_read_b128 v[80:83], v146
	ds_read_b128 v[84:87], v150
	ds_read_b128 v[88:91], v147
	ds_read_b128 v[92:95], v151
	ds_read_b128 v[96:99], v144 offset:24576
	ds_read_b128 v[100:103], v148 offset:24576
	ds_read_b128 v[104:107], v145 offset:24576
	ds_read_b128 v[108:111], v149 offset:24576
	ds_read_b128 v[112:115], v146 offset:24576
	ds_read_b128 v[116:119], v150 offset:24576
	ds_read_b128 v[120:123], v147 offset:24576
	ds_read_b128 v[124:127], v151 offset:24576
	s_waitcnt lgkmcnt(14)
	v_mfma_f32_32x32x16_bf16 v[16:31], v[64:67], v[68:71], v[16:31]
	s_waitcnt lgkmcnt(12)
	v_mfma_f32_32x32x16_bf16 v[16:31], v[72:75], v[76:79], v[16:31]
	s_waitcnt lgkmcnt(10)
	v_mfma_f32_32x32x16_bf16 v[16:31], v[80:83], v[84:87], v[16:31]
	s_waitcnt lgkmcnt(8)
	v_mfma_f32_32x32x16_bf16 v[16:31], v[88:91], v[92:95], v[16:31]
	s_waitcnt lgkmcnt(6)
	v_mfma_f32_32x32x16_bf16 v[16:31], v[96:99], v[100:103], v[16:31]
	s_waitcnt lgkmcnt(4)
	v_mfma_f32_32x32x16_bf16 v[16:31], v[104:107], v[108:111], v[16:31]
	s_waitcnt lgkmcnt(2)
	v_mfma_f32_32x32x16_bf16 v[16:31], v[112:115], v[116:119], v[16:31]
	s_waitcnt lgkmcnt(0)
	v_mfma_f32_32x32x16_bf16 v[16:31], v[120:123], v[124:127], v[16:31]
	s_waitcnt vmcnt(6)
	s_barrier
	s_mov_b32 s12, 14336
	s_mov_b32 s14, 14848
	s_mov_b32 s16, 3584
	s_mov_b32 s18, 3712
	s_add_u32 m0, s88, 98304
	v_lshl_add_u64 v[160:161], v[152:153], 0, s[12:13]
	global_load_lds_dwordx4 v[160:161], off
	s_add_u32 m0, s88, 106496
	v_lshl_add_u64 v[162:163], v[154:155], 0, s[16:17]
	global_load_lds_dwordx4 v[162:163], off
	s_add_u32 m0, s88, 114688
	v_lshl_add_u64 v[164:165], v[156:157], 0, s[16:17]
	global_load_lds_dwordx4 v[164:165], off
	s_add_u32 m0, s88, 122880
	v_lshl_add_u64 v[160:161], v[152:153], 0, s[14:15]
	global_load_lds_dwordx4 v[160:161], off
	s_add_u32 m0, s88, 131072
	v_lshl_add_u64 v[162:163], v[154:155], 0, s[18:19]
	global_load_lds_dwordx4 v[162:163], off
	s_add_u32 m0, s88, 139264
	v_lshl_add_u64 v[164:165], v[156:157], 0, s[18:19]
	global_load_lds_dwordx4 v[164:165], off
	ds_read_b128 v[64:67], v128
	ds_read_b128 v[68:71], v132
	ds_read_b128 v[72:75], v129
	ds_read_b128 v[76:79], v133
	ds_read_b128 v[80:83], v130
	ds_read_b128 v[84:87], v134
	ds_read_b128 v[88:91], v131
	ds_read_b128 v[92:95], v135
	ds_read_b128 v[96:99], v128 offset:24576
	ds_read_b128 v[100:103], v132 offset:24576
	ds_read_b128 v[104:107], v129 offset:24576
	ds_read_b128 v[108:111], v133 offset:24576
	ds_read_b128 v[112:115], v130 offset:24576
	ds_read_b128 v[116:119], v134 offset:24576
	ds_read_b128 v[120:123], v131 offset:24576
	ds_read_b128 v[124:127], v135 offset:24576
	s_waitcnt lgkmcnt(14)
	v_mfma_f32_32x32x16_bf16 v[16:31], v[64:67], v[68:71], v[16:31]
	s_waitcnt lgkmcnt(12)
	v_mfma_f32_32x32x16_bf16 v[16:31], v[72:75], v[76:79], v[16:31]
	s_waitcnt lgkmcnt(10)
	v_mfma_f32_32x32x16_bf16 v[16:31], v[80:83], v[84:87], v[16:31]
	s_waitcnt lgkmcnt(8)
	v_mfma_f32_32x32x16_bf16 v[16:31], v[88:91], v[92:95], v[16:31]
	s_waitcnt lgkmcnt(6)
	v_mfma_f32_32x32x16_bf16 v[16:31], v[96:99], v[100:103], v[16:31]
	s_waitcnt lgkmcnt(4)
	v_mfma_f32_32x32x16_bf16 v[16:31], v[104:107], v[108:111], v[16:31]
	s_waitcnt lgkmcnt(2)
	v_mfma_f32_32x32x16_bf16 v[16:31], v[112:115], v[116:119], v[16:31]
	s_waitcnt lgkmcnt(0)
	v_mfma_f32_32x32x16_bf16 v[16:31], v[120:123], v[124:127], v[16:31]
	s_waitcnt vmcnt(6)
	s_barrier
	s_mov_b32 s12, 15360
	s_mov_b32 s14, 15872
	s_mov_b32 s16, 3840
	s_mov_b32 s18, 3968
	s_add_u32 m0, s88, 0
	v_lshl_add_u64 v[160:161], v[152:153], 0, s[12:13]
	global_load_lds_dwordx4 v[160:161], off
	s_add_u32 m0, s88, 8192
	v_lshl_add_u64 v[162:163], v[154:155], 0, s[16:17]
	global_load_lds_dwordx4 v[162:163], off
	s_add_u32 m0, s88, 16384
	v_lshl_add_u64 v[164:165], v[156:157], 0, s[16:17]
	global_load_lds_dwordx4 v[164:165], off
	s_add_u32 m0, s88, 24576
	v_lshl_add_u64 v[160:161], v[152:153], 0, s[14:15]
	global_load_lds_dwordx4 v[160:161], off
	s_add_u32 m0, s88, 32768
	v_lshl_add_u64 v[162:163], v[154:155], 0, s[18:19]
	global_load_lds_dwordx4 v[162:163], off
	s_add_u32 m0, s88, 40960
	v_lshl_add_u64 v[164:165], v[156:157], 0, s[18:19]
	global_load_lds_dwordx4 v[164:165], off
	ds_read_b128 v[64:67], v136
	ds_read_b128 v[68:71], v140
	ds_read_b128 v[72:75], v137
	ds_read_b128 v[76:79], v141
	ds_read_b128 v[80:83], v138
	ds_read_b128 v[84:87], v142
	ds_read_b128 v[88:91], v139
	ds_read_b128 v[92:95], v143
	ds_read_b128 v[96:99], v136 offset:24576
	ds_read_b128 v[100:103], v140 offset:24576
	ds_read_b128 v[104:107], v137 offset:24576
	ds_read_b128 v[108:111], v141 offset:24576
	ds_read_b128 v[112:115], v138 offset:24576
	ds_read_b128 v[116:119], v142 offset:24576
	ds_read_b128 v[120:123], v139 offset:24576
	ds_read_b128 v[124:127], v143 offset:24576
	s_waitcnt lgkmcnt(14)
	v_mfma_f32_32x32x16_bf16 v[16:31], v[64:67], v[68:71], v[16:31]
	s_waitcnt lgkmcnt(12)
	v_mfma_f32_32x32x16_bf16 v[16:31], v[72:75], v[76:79], v[16:31]
	s_waitcnt lgkmcnt(10)
	v_mfma_f32_32x32x16_bf16 v[16:31], v[80:83], v[84:87], v[16:31]
	s_waitcnt lgkmcnt(8)
	v_mfma_f32_32x32x16_bf16 v[16:31], v[88:91], v[92:95], v[16:31]
	s_waitcnt lgkmcnt(6)
	v_mfma_f32_32x32x16_bf16 v[16:31], v[96:99], v[100:103], v[16:31]
	s_waitcnt lgkmcnt(4)
	v_mfma_f32_32x32x16_bf16 v[16:31], v[104:107], v[108:111], v[16:31]
	s_waitcnt lgkmcnt(2)
	v_mfma_f32_32x32x16_bf16 v[16:31], v[112:115], v[116:119], v[16:31]
	s_waitcnt lgkmcnt(0)
	v_mfma_f32_32x32x16_bf16 v[16:31], v[120:123], v[124:127], v[16:31]
	s_waitcnt vmcnt(6)
	s_barrier
	s_add_u32 m0, s88, 49152
	v_lshl_add_u64 v[160:161], v[158:159], 0, 0
	global_load_lds_dwordx4 v[160:161], off
	s_movk_i32 s12, 0x80
	s_add_u32 m0, s88, 57344
	v_lshl_add_u64 v[162:163], v[158:159], 0, s[12:13]
	global_load_lds_dwordx4 v[162:163], off
	ds_read_b128 v[64:67], v144
	ds_read_b128 v[68:71], v148
	ds_read_b128 v[72:75], v145
	ds_read_b128 v[76:79], v149
	ds_read_b128 v[80:83], v146
	ds_read_b128 v[84:87], v150
	ds_read_b128 v[88:91], v147
	ds_read_b128 v[92:95], v151
	ds_read_b128 v[96:99], v144 offset:24576
	ds_read_b128 v[100:103], v148 offset:24576
	ds_read_b128 v[104:107], v145 offset:24576
	ds_read_b128 v[108:111], v149 offset:24576
	ds_read_b128 v[112:115], v146 offset:24576
	ds_read_b128 v[116:119], v150 offset:24576
	ds_read_b128 v[120:123], v147 offset:24576
	ds_read_b128 v[124:127], v151 offset:24576
	s_waitcnt lgkmcnt(14)
	v_mfma_f32_32x32x16_bf16 v[16:31], v[64:67], v[68:71], v[16:31]
	s_waitcnt lgkmcnt(12)
	v_mfma_f32_32x32x16_bf16 v[16:31], v[72:75], v[76:79], v[16:31]
	s_waitcnt lgkmcnt(10)
	v_mfma_f32_32x32x16_bf16 v[16:31], v[80:83], v[84:87], v[16:31]
	s_waitcnt lgkmcnt(8)
	v_mfma_f32_32x32x16_bf16 v[16:31], v[88:91], v[92:95], v[16:31]
	s_waitcnt lgkmcnt(6)
	v_mfma_f32_32x32x16_bf16 v[16:31], v[96:99], v[100:103], v[16:31]
	s_waitcnt lgkmcnt(4)
	v_mfma_f32_32x32x16_bf16 v[16:31], v[104:107], v[108:111], v[16:31]
	s_waitcnt lgkmcnt(2)
	v_mfma_f32_32x32x16_bf16 v[16:31], v[112:115], v[116:119], v[16:31]
	s_waitcnt lgkmcnt(0)
	v_mfma_f32_32x32x16_bf16 v[16:31], v[120:123], v[124:127], v[16:31]
	s_waitcnt vmcnt(2)
	s_barrier
	ds_read_b128 v[64:67], v128
	ds_read_b128 v[68:71], v132
	ds_read_b128 v[72:75], v129
	ds_read_b128 v[76:79], v133
	ds_read_b128 v[80:83], v130
	ds_read_b128 v[84:87], v134
	ds_read_b128 v[88:91], v131
	ds_read_b128 v[92:95], v135
	ds_read_b128 v[96:99], v128 offset:24576
	ds_read_b128 v[100:103], v132 offset:24576
	ds_read_b128 v[104:107], v129 offset:24576
	ds_read_b128 v[108:111], v133 offset:24576
	ds_read_b128 v[112:115], v130 offset:24576
	ds_read_b128 v[116:119], v134 offset:24576
	ds_read_b128 v[120:123], v131 offset:24576
	ds_read_b128 v[124:127], v135 offset:24576
	s_waitcnt lgkmcnt(14)
	v_mfma_f32_32x32x16_bf16 v[16:31], v[64:67], v[68:71], v[16:31]
	s_waitcnt lgkmcnt(12)
	v_mfma_f32_32x32x16_bf16 v[16:31], v[72:75], v[76:79], v[16:31]
	s_waitcnt lgkmcnt(10)
	v_mfma_f32_32x32x16_bf16 v[16:31], v[80:83], v[84:87], v[16:31]
	s_waitcnt lgkmcnt(8)
	v_mfma_f32_32x32x16_bf16 v[16:31], v[88:91], v[92:95], v[16:31]
	s_waitcnt lgkmcnt(6)
	v_mfma_f32_32x32x16_bf16 v[16:31], v[96:99], v[100:103], v[16:31]
	s_waitcnt lgkmcnt(4)
	v_mfma_f32_32x32x16_bf16 v[16:31], v[104:107], v[108:111], v[16:31]
	s_waitcnt lgkmcnt(2)
	v_mfma_f32_32x32x16_bf16 v[16:31], v[112:115], v[116:119], v[16:31]
	s_waitcnt lgkmcnt(0)
	v_mfma_f32_32x32x16_bf16 v[16:31], v[120:123], v[124:127], v[16:31]
	s_lshr_b32 s8, s29, 2
	s_and_b32 s9, s29, 3
	s_lshr_b32 s10, s9, 1
	s_lshl_b32 s10, s10, 13
	s_lshl_b32 s8, s8, 12
	s_add_u32 s10, s10, s8
	s_add_u32 s10, s10, 98304
	s_and_b32 s9, s9, 1
	s_lshl_b32 s9, s9, 2
	v_lshlrev_b32_e32 v184, 9, v2
	v_and_b32_e32 v185, 7, v1
	v_lshl_add_u32 v184, v185, 1, v184
	v_add_u32_e32 v184, s10, v184
	v_lshrrev_b32_e32 v185, 3, v1
	v_or_b32_e32 v185, s9, v185
	v_lshlrev_b32_e32 v186, 1, v2
	v_xor_b32_e32 v185, v185, v186
	v_lshl_add_u32 v204, v185, 4, v184
	v_xor_b32_e32 v186, 1, v185
	v_lshl_add_u32 v205, v186, 4, v184
	v_xor_b32_e32 v186, 4, v185
	v_lshl_add_u32 v206, v186, 4, v184
	v_xor_b32_e32 v186, 5, v185
	v_lshl_add_u32 v207, v186, 4, v184
	s_nop 7
	v_add_f32_e32 v188, v16, v166
	v_mul_f32_e32 v189, 0xbfb8aa3b, v188
	v_exp_f32_e32 v189, v189
	s_nop 0
	v_add_f32_e32 v189, 1.0, v189
	v_rcp_f32_e32 v189, v189
	s_nop 0
	v_mul_f32_e32 v188, v188, v189
	v_cvt_pk_bf16_f32 v188, v188, v188
	ds_write_b16 v204, v188
	v_add_f32_e32 v190, v17, v166
	v_mul_f32_e32 v191, 0xbfb8aa3b, v190
	v_exp_f32_e32 v191, v191
	s_nop 0
	v_add_f32_e32 v191, 1.0, v191
	v_rcp_f32_e32 v191, v191
	s_nop 0
	v_mul_f32_e32 v190, v190, v191
	v_cvt_pk_bf16_f32 v190, v190, v190
	ds_write_b16 v204, v190 offset:128
	v_add_f32_e32 v192, v18, v166
	v_mul_f32_e32 v193, 0xbfb8aa3b, v192
	v_exp_f32_e32 v193, v193
	s_nop 0
	v_add_f32_e32 v193, 1.0, v193
	v_rcp_f32_e32 v193, v193
	s_nop 0
	v_mul_f32_e32 v192, v192, v193
	v_cvt_pk_bf16_f32 v192, v192, v192
	ds_write_b16 v205, v192 offset:256
	v_add_f32_e32 v194, v19, v166
	v_mul_f32_e32 v195, 0xbfb8aa3b, v194
	v_exp_f32_e32 v195, v195
	s_nop 0
	v_add_f32_e32 v195, 1.0, v195
	v_rcp_f32_e32 v195, v195
	s_nop 0
	v_mul_f32_e32 v194, v194, v195
	v_cvt_pk_bf16_f32 v194, v194, v194
	ds_write_b16 v205, v194 offset:384
	v_add_f32_e32 v188, v20, v166
	v_mul_f32_e32 v189, 0xbfb8aa3b, v188
	v_exp_f32_e32 v189, v189
	s_nop 0
	v_add_f32_e32 v189, 1.0, v189
	v_rcp_f32_e32 v189, v189
	s_nop 0
	v_mul_f32_e32 v188, v188, v189
	v_cvt_pk_bf16_f32 v188, v188, v188
	ds_write_b16 v206, v188 offset:1024
	v_add_f32_e32 v190, v21, v166
	v_mul_f32_e32 v191, 0xbfb8aa3b, v190
	v_exp_f32_e32 v191, v191
	s_nop 0
	v_add_f32_e32 v191, 1.0, v191
	v_rcp_f32_e32 v191, v191
	s_nop 0
	v_mul_f32_e32 v190, v190, v191
	v_cvt_pk_bf16_f32 v190, v190, v190
	ds_write_b16 v206, v190 offset:1152
	v_add_f32_e32 v192, v22, v166
	v_mul_f32_e32 v193, 0xbfb8aa3b, v192
	v_exp_f32_e32 v193, v193
	s_nop 0
	v_add_f32_e32 v193, 1.0, v193
	v_rcp_f32_e32 v193, v193
	s_nop 0
	v_mul_f32_e32 v192, v192, v193
	v_cvt_pk_bf16_f32 v192, v192, v192
	ds_write_b16 v207, v192 offset:1280
	v_add_f32_e32 v194, v23, v166
	v_mul_f32_e32 v195, 0xbfb8aa3b, v194
	v_exp_f32_e32 v195, v195
	s_nop 0
	v_add_f32_e32 v195, 1.0, v195
	v_rcp_f32_e32 v195, v195
	s_nop 0
	v_mul_f32_e32 v194, v194, v195
	v_cvt_pk_bf16_f32 v194, v194, v194
	ds_write_b16 v207, v194 offset:1408
	v_add_f32_e32 v188, v24, v166
	v_mul_f32_e32 v189, 0xbfb8aa3b, v188
	v_exp_f32_e32 v189, v189
	s_nop 0
	v_add_f32_e32 v189, 1.0, v189
	v_rcp_f32_e32 v189, v189
	s_nop 0
	v_mul_f32_e32 v188, v188, v189
	v_cvt_pk_bf16_f32 v188, v188, v188
	ds_write_b16 v204, v188 offset:2048
	v_add_f32_e32 v190, v25, v166
	v_mul_f32_e32 v191, 0xbfb8aa3b, v190
	v_exp_f32_e32 v191, v191
	s_nop 0
	v_add_f32_e32 v191, 1.0, v191
	v_rcp_f32_e32 v191, v191
	s_nop 0
	v_mul_f32_e32 v190, v190, v191
	v_cvt_pk_bf16_f32 v190, v190, v190
	ds_write_b16 v204, v190 offset:2176
	v_add_f32_e32 v192, v26, v166
	v_mul_f32_e32 v193, 0xbfb8aa3b, v192
	v_exp_f32_e32 v193, v193
	s_nop 0
	v_add_f32_e32 v193, 1.0, v193
	v_rcp_f32_e32 v193, v193
	s_nop 0
	v_mul_f32_e32 v192, v192, v193
	v_cvt_pk_bf16_f32 v192, v192, v192
	ds_write_b16 v205, v192 offset:2304
	v_add_f32_e32 v194, v27, v166
	v_mul_f32_e32 v195, 0xbfb8aa3b, v194
	v_exp_f32_e32 v195, v195
	s_nop 0
	v_add_f32_e32 v195, 1.0, v195
	v_rcp_f32_e32 v195, v195
	s_nop 0
	v_mul_f32_e32 v194, v194, v195
	v_cvt_pk_bf16_f32 v194, v194, v194
	ds_write_b16 v205, v194 offset:2432
	v_add_f32_e32 v188, v28, v166
	v_mul_f32_e32 v189, 0xbfb8aa3b, v188
	v_exp_f32_e32 v189, v189
	s_nop 0
	v_add_f32_e32 v189, 1.0, v189
	v_rcp_f32_e32 v189, v189
	s_nop 0
	v_mul_f32_e32 v188, v188, v189
	v_cvt_pk_bf16_f32 v188, v188, v188
	ds_write_b16 v206, v188 offset:3072
	v_add_f32_e32 v190, v29, v166
	v_mul_f32_e32 v191, 0xbfb8aa3b, v190
	v_exp_f32_e32 v191, v191
	s_nop 0
	v_add_f32_e32 v191, 1.0, v191
	v_rcp_f32_e32 v191, v191
	s_nop 0
	v_mul_f32_e32 v190, v190, v191
	v_cvt_pk_bf16_f32 v190, v190, v190
	ds_write_b16 v206, v190 offset:3200
	v_add_f32_e32 v192, v30, v166
	v_mul_f32_e32 v193, 0xbfb8aa3b, v192
	v_exp_f32_e32 v193, v193
	s_nop 0
	v_add_f32_e32 v193, 1.0, v193
	v_rcp_f32_e32 v193, v193
	s_nop 0
	v_mul_f32_e32 v192, v192, v193
	v_cvt_pk_bf16_f32 v192, v192, v192
	ds_write_b16 v207, v192 offset:3328
	v_add_f32_e32 v194, v31, v166
	v_mul_f32_e32 v195, 0xbfb8aa3b, v194
	v_exp_f32_e32 v195, v195
	s_nop 0
	v_add_f32_e32 v195, 1.0, v195
	v_rcp_f32_e32 v195, v195
	s_nop 0
	v_mul_f32_e32 v194, v194, v195
	v_cvt_pk_bf16_f32 v194, v194, v194
	ds_write_b16 v207, v194 offset:3456
	s_waitcnt vmcnt(0) lgkmcnt(0)
	s_barrier
	s_cmp_lt_u32 s29, 4
	s_cbranch_scc0 .Lnc_skip2
	s_lshr_b32 s8, s29, 1
	s_and_b32 s9, s29, 1
	s_lshl_b32 s10, s8, 12
	s_add_u32 s10, s10, 98304
	s_lshl_b32 s11, s9, 12
	s_add_u32 s11, s11, 49152
	v_add_u32_e32 v184, s10, v200
	v_add_u32_e32 v188, s11, v200
	v_add_u32_e32 v185, s10, v201
	v_add_u32_e32 v189, s11, v201
	v_add_u32_e32 v186, s10, v202
	v_add_u32_e32 v190, s11, v202
	v_add_u32_e32 v187, s10, v203
	v_add_u32_e32 v191, s11, v203
	ds_read_b128 v[64:67], v184
	ds_read_b128 v[68:71], v188
	ds_read_b128 v[72:75], v185
	ds_read_b128 v[76:79], v189
	ds_read_b128 v[80:83], v186
	ds_read_b128 v[84:87], v190
	ds_read_b128 v[88:91], v187
	ds_read_b128 v[92:95], v191
	ds_read_b128 v[96:99], v184 offset:8192
	ds_read_b128 v[100:103], v188 offset:8192
	ds_read_b128 v[104:107], v185 offset:8192
	ds_read_b128 v[108:111], v189 offset:8192
	ds_read_b128 v[112:115], v186 offset:8192
	ds_read_b128 v[116:119], v190 offset:8192
	ds_read_b128 v[120:123], v187 offset:8192
	ds_read_b128 v[124:127], v191 offset:8192
	s_waitcnt lgkmcnt(14)
	v_mfma_f32_32x32x16_bf16 v[32:47], v[64:67], v[68:71], 0
	s_waitcnt lgkmcnt(12)
	v_mfma_f32_32x32x16_bf16 v[32:47], v[72:75], v[76:79], v[32:47]
	s_waitcnt lgkmcnt(10)
	v_mfma_f32_32x32x16_bf16 v[32:47], v[80:83], v[84:87], v[32:47]
	s_waitcnt lgkmcnt(8)
	v_mfma_f32_32x32x16_bf16 v[32:47], v[88:91], v[92:95], v[32:47]
	s_waitcnt lgkmcnt(6)
	v_mfma_f32_32x32x16_bf16 v[32:47], v[96:99], v[100:103], v[32:47]
	s_waitcnt lgkmcnt(4)
	v_mfma_f32_32x32x16_bf16 v[32:47], v[104:107], v[108:111], v[32:47]
	s_waitcnt lgkmcnt(2)
	v_mfma_f32_32x32x16_bf16 v[32:47], v[112:115], v[116:119], v[32:47]
	s_waitcnt lgkmcnt(0)
	v_mfma_f32_32x32x16_bf16 v[32:47], v[120:123], v[124:127], v[32:47]
	s_cmp_eq_u32 s34, 0x7f
	s_cselect_b32 s10, 1, 0
	s_and_b32 s10, s10, s8
	s_cmp_eq_u32 s10, 1
	s_cbranch_scc1 .Lnc_skip2
	s_lshl_b32 s10, s8, 3
	s_lshr_b32 s11, s35, 2
	s_add_u32 s10, s10, s11
	v_add_u32_e32 v184, s10, v2
	s_lshl_b32 s11, s9, 6
	v_lshl_add_u32 v185, v1, 1, s11
	s_mov_b32 s8, 0x80808081
	v_mul_hi_u32 v191, v184, s8
	v_lshrrev_b32_e32 v191, 7, v191
	v_mul_u32_u24_e32 v192, 0xff, v191
	v_sub_u32_e32 v192, v184, v192
	v_lshlrev_b32_e32 v191, 17, v191
	v_lshl_add_u32 v191, v192, 7, v191
	v_add_u32_e32 v186, v191, v185
	v_add_u32_e32 v190, 2, v184
	v_mul_hi_u32 v191, v190, s8
	v_lshrrev_b32_e32 v191, 7, v191
	v_mul_u32_u24_e32 v192, 0xff, v191
	v_sub_u32_e32 v192, v190, v192
	v_lshlrev_b32_e32 v191, 17, v191
	v_lshl_add_u32 v191, v192, 7, v191
	v_add_u32_e32 v187, v191, v185
	v_add_u32_e32 v190, 4, v184
	v_mul_hi_u32 v191, v190, s8
	v_lshrrev_b32_e32 v191, 7, v191
	v_mul_u32_u24_e32 v192, 0xff, v191
	v_sub_u32_e32 v192, v190, v192
	v_lshlrev_b32_e32 v191, 17, v191
	v_lshl_add_u32 v191, v192, 7, v191
	v_add_u32_e32 v188, v191, v185
	v_add_u32_e32 v190, 6, v184
	v_mul_hi_u32 v191, v190, s8
	v_lshrrev_b32_e32 v191, 7, v191
	v_mul_u32_u24_e32 v192, 0xff, v191
	v_sub_u32_e32 v192, v190, v192
	v_lshlrev_b32_e32 v191, 17, v191
	v_lshl_add_u32 v191, v192, 7, v191
	v_add_u32_e32 v189, v191, v185
	s_nop 7
	s_nop 3
	v_cvt_pk_bf16_f32 v197, v32, v32
	global_store_short v186, v197, s[20:21]
	v_cvt_pk_bf16_f32 v198, v33, v33
	v_add_u32_e32 v194, 32768, v186
	global_store_short v194, v198, s[20:21]
	v_cvt_pk_bf16_f32 v197, v34, v34
	v_add_u32_e32 v195, 65536, v186
	global_store_short v195, v197, s[20:21]
	v_cvt_pk_bf16_f32 v198, v35, v35
	v_add_u32_e32 v196, 98304, v186
	global_store_short v196, v198, s[20:21]
	v_cvt_pk_bf16_f32 v197, v36, v36
	global_store_short v187, v197, s[20:21]
	v_cvt_pk_bf16_f32 v198, v37, v37
	v_add_u32_e32 v194, 32768, v187
	global_store_short v194, v198, s[20:21]
	v_cvt_pk_bf16_f32 v197, v38, v38
	v_add_u32_e32 v195, 65536, v187
	global_store_short v195, v197, s[20:21]
	v_cvt_pk_bf16_f32 v198, v39, v39
	v_add_u32_e32 v196, 98304, v187
	global_store_short v196, v198, s[20:21]
	v_cvt_pk_bf16_f32 v197, v40, v40
	global_store_short v188, v197, s[20:21]
	v_cvt_pk_bf16_f32 v198, v41, v41
	v_add_u32_e32 v194, 32768, v188
	global_store_short v194, v198, s[20:21]
	v_cvt_pk_bf16_f32 v197, v42, v42
	v_add_u32_e32 v195, 65536, v188
	global_store_short v195, v197, s[20:21]
	v_cvt_pk_bf16_f32 v198, v43, v43
	v_add_u32_e32 v196, 98304, v188
	global_store_short v196, v198, s[20:21]
	v_cvt_pk_bf16_f32 v197, v44, v44
	global_store_short v189, v197, s[20:21]
	v_cvt_pk_bf16_f32 v198, v45, v45
	v_add_u32_e32 v194, 32768, v189
	global_store_short v194, v198, s[20:21]
	v_cvt_pk_bf16_f32 v197, v46, v46
	v_add_u32_e32 v195, 65536, v189
	global_store_short v195, v197, s[20:21]
	v_cvt_pk_bf16_f32 v198, v47, v47
	v_add_u32_e32 v196, 98304, v189
	global_store_short v196, v198, s[20:21]
.Lnc_skip2:
	s_add_u32 s30, s30, s42
	s_cmpk_lt_u32 s30, 0x100
	s_cbranch_scc1 .Lnc_tile
.Lnc_done:
.LBB0_4084:
	s_cmp_lt_i32 s45, 14
	s_cbranch_scc1 .LBB0_4138
	s_waitcnt vmcnt(0) lgkmcnt(0)
	s_barrier
	v_mbcnt_hi_u32_b32 v0, -1, v210
	v_cmp_eq_u32_e32 vcc, 0, v0
	s_and_b64 s[4:5], s[46:47], vcc
	s_and_saveexec_b64 s[2:3], s[4:5]
	s_cbranch_execz .Lfb12_join
	v_mov_b32_e32 v0, 0x24400
	ds_read_b32 v1, v0
	ds_read_b32 v2, v0 offset:4
	ds_read_b32 v3, v0 offset:8
	s_waitcnt lgkmcnt(0)
	v_readfirstlane_b32 s4, v1
	v_readfirstlane_b32 s5, v2
	v_readfirstlane_b32 s6, v3
	s_add_u32 s7, s6, 1
	v_mov_b32_e32 v4, s7
	ds_write_b32 v0, v4 offset:8
	s_mul_i32 s8, s7, s4
	s_mul_i32 s9, s7, s5
	s_lshl_b32 s10, s23, 7
	s_add_u32 s10, s10, 0x3600
	v_mov_b32_e32 v1, s10
	v_mov_b32_e32 v2, 1
	global_atomic_add v3, v1, v2, s[40:41] sc0
	s_waitcnt vmcnt(0)
	v_readfirstlane_b32 s11, v3
	s_add_u32 s11, s11, 1
	v_mov_b32_e32 v1, 0x3e00
	s_cmp_lg_u32 s11, s8
	s_cbranch_scc1 .Lfb12_spin
	buffer_wbl2 sc1
	s_waitcnt vmcnt(0)
	global_atomic_add v1, v2, s[40:41]

.LBB0_4138:
	s_cmp_gt_i32 s44, 13
	s_cselect_b64 s[2:3], -1, 0
	s_cmp_lt_i32 s45, 14
	s_cselect_b64 s[4:5], -1, 0
	s_or_b64 s[2:3], s[2:3], s[4:5]
	s_and_b64 vcc, exec, s[2:3]
	s_cbranch_vccnz .LBB0_4216
.LBB0_4162:
	s_cmp_lt_i32 s45, 15
	s_cbranch_scc1 .LBB0_4216
.LBB0_4216:
	s_cmp_gt_i32 s44, 14
	s_cselect_b64 s[2:3], -1, 0
	s_cmp_lt_i32 s45, 15
	s_cselect_b64 s[4:5], -1, 0
	s_or_b64 s[2:3], s[2:3], s[4:5]
	s_and_b64 vcc, exec, s[2:3]
	s_cbranch_vccnz .LBB0_4361
	v_mbcnt_hi_u32_b32 v38, -1, v210
	v_mov_b32_e32 v0, v38
	s_mov_b32 s49, 0
	v_add_u32_e32 v39, s70, v0
	s_cmpk_gt_i32 s22, 0x1ff
	v_readfirstlane_b32 s2, v39
	s_cbranch_scc1 .LBB0_4307
	s_abs_i32 s60, s42
	v_cvt_f32_u32_e32 v1, s60
	s_sub_i32 s4, 0, s60
	v_and_b32_e32 v3, 64, v38
	s_load_dwordx2 s[50:51], s[0:1], 0x1f0
	v_rcp_iflag_f32_e32 v1, v1
	v_xor_b32_e32 v2, 32, v38
	v_add_u32_e32 v3, 64, v3
	v_cmp_lt_i32_e32 vcc, v2, v3
	v_mul_f32_e32 v1, 0x4f7ffffe, v1
	v_cvt_u32_f32_e32 v1, v1
	s_ashr_i32 s58, s2, 6
	s_movk_i32 s2, 0x800
	v_cndmask_b32_e32 v2, v38, v2, vcc
	v_readfirstlane_b32 s5, v1
	s_mul_i32 s4, s4, s5
	s_mul_hi_u32 s4, s5, s4
	s_add_i32 s62, s5, s4
	s_lshl_b32 s4, s71, 3
	s_and_b32 s4, s4, 0xfffffe00
	s_lshl_b32 s59, s58, 13
	v_cmp_gt_i32_e64 s[2:3], s2, v39
	v_lshlrev_b32_e32 v40, 2, v2
	s_ashr_i32 s61, s42, 31
	v_lshl_add_u32 v41, v0, 3, s4
	v_mov_b32_e32 v33, 0
	s_movk_i32 s63, 0x90
	s_mov_b32 s64, 0x10000
	s_movk_i32 s65, 0x5ff
	v_mov_b32_e32 v42, 0xff800000
	v_mov_b32_e32 v43, 0xc0400000
	s_mov_b32 s66, s22
	s_branch .LBB0_4220
